# attention softmax: rare O-rescale path moved out of line after the tile loop so the common path has no taken branch; loop re-aligned to 8-byte instruction boundaries
# baseline (speedup 1.0000x reference)
; __device__ __forceinline__ void partialSM(f32x16& p0, f32x16& p1, float& m_reg, float& mn, float& alpha) {
;     constexpr float Cc = SCALE * 1.4426950408889634f;
;     float pmax = p0[0];
; #pragma unroll
;     for (int r = 1; r < 16; ++r) pmax = fmaxf(pmax, p0[r]);
; #pragma unroll
;     for (int r = 0; r < 16; ++r) pmax = fmaxf(pmax, p1[r]);
;     { auto rr = __builtin_amdgcn_permlane32_swap(__float_as_uint(pmax), __float_as_uint(pmax), false, false);
;       pmax = fmaxf(__uint_as_float(rr[0]), __uint_as_float(rr[1])); }
;     if (__builtin_expect(__all(pmax - m_reg <= THR / SCALE), 1)) { mn = m_reg; alpha = 1.f; }
;     else { mn = fmaxf(m_reg, pmax); alpha = __builtin_amdgcn_exp2f((m_reg - mn) * Cc); m_reg = mn; }
;     const float mnC = -mn * Cc;
;     { typedef float f32x2 __attribute__((ext_vector_type(2))); const f32x2 c2 = {Cc, Cc}, m2 = {mnC, mnC};
; #pragma unroll
;       for (int r = 0; r < 16; r += 2) { f32x2 t = {p0[r], p0[r + 1]}; t = __builtin_elementwise_fma(t, c2, m2); p0[r] = t.x; p0[r + 1] = t.y; }
; #pragma unroll
;       for (int r = 0; r < 16; r += 2) { f32x2 t = {p1[r], p1[r + 1]}; t = __builtin_elementwise_fma(t, c2, m2); p1[r] = t.x; p1[r + 1] = t.y; } }
; #pragma unroll
;     for (int r = 0; r < 16; ++r) p0[r] = __builtin_amdgcn_exp2f(p0[r]);
; }
; __device__ __forceinline__ void finishSM(f32x16& p0, f32x16& p1, float alpha, float& l_reg, bf16x8& pa0, bf16x8& pa1, bf16x8& pa2, bf16x8& pa3) {
; #pragma unroll
;     for (int r = 0; r < 16; ++r) p1[r] = __builtin_amdgcn_exp2f(p1[r]);
;     float ps;
;     { typedef float f32x2 __attribute__((ext_vector_type(2))); f32x2 s0 = {p0[0], p0[1]}, s1 = {p1[0], p1[1]};
; #pragma unroll
;       for (int r = 2; r < 16; r += 2) { s0 += (f32x2){p0[r], p0[r + 1]}; s1 += (f32x2){p1[r], p1[r + 1]}; }
;       s0 += s1; ps = s0.x + s0.y; }
;     { auto rr = __builtin_amdgcn_permlane32_swap(__float_as_uint(ps), __float_as_uint(ps), false, false);
;       ps = __uint_as_float(rr[0]) + __uint_as_float(rr[1]); }
;     l_reg = l_reg * alpha + ps;
;     ...
;     PK4(p0, 0, pa0); PK4(p0, 8, pa1); PK4(p1, 0, pa2); PK4(p1, 8, pa3);
.LA_nosw:
	v_add_u32_e32 v202, s18, v235
	v_max_f32_e32 v212, v66, v67
	v_max_f32_e32 v213, v82, v83
	v_max3_f32 v212, v212, v68, v69
	v_max3_f32 v213, v213, v84, v85
	v_max3_f32 v212, v212, v70, v71
	v_max3_f32 v213, v213, v86, v87
	v_max3_f32 v212, v212, v72, v73
	v_max3_f32 v213, v213, v88, v89
	v_max3_f32 v212, v212, v74, v75
	v_max3_f32 v213, v213, v90, v91
	v_max3_f32 v212, v212, v76, v77
	v_max3_f32 v213, v213, v92, v93
	v_max3_f32 v212, v212, v78, v79
	v_max3_f32 v213, v213, v94, v95
	v_max3_f32 v212, v212, v80, v81
	v_max3_f32 v213, v213, v96, v97
	v_max_f32_e32 v212, v212, v213
	v_mov_b32_e32 v213, v212
	s_nop 1
	v_permlane32_swap_b32_e32 v212, v213
	v_max_f32_e32 v212, v212, v213
	v_sub_f32_e32 v214, v212, v141
	v_cmp_ge_f32_e32 vcc, s67, v214
	v_max_f32_e32 v212, v141, v212
	v_sub_f32_e64 v214, v141, v212
	v_mul_f32_e32 v214, 0x3e16c740, v214
	v_exp_f32_e64 v215, v214
	s_cmp_eq_u64 vcc, exec
	s_cselect_b64 s[58:59], -1, 0
	v_cndmask_b32_e64 v141, v212, v141, s[58:59]
	v_cndmask_b32_e64 v215, v215, 1.0, s[58:59]
	v_mul_f32_e32 v216, 0xbe16c740, v141
	v_fma_f32 v66, v66, s52, v216
	v_fma_f32 v67, v67, s52, v216
	v_fma_f32 v68, v68, s52, v216
	v_fma_f32 v69, v69, s52, v216
	v_fma_f32 v70, v70, s52, v216
	v_fma_f32 v71, v71, s52, v216
	v_fma_f32 v72, v72, s52, v216
	v_fma_f32 v73, v73, s52, v216
	v_fma_f32 v74, v74, s52, v216
	v_fma_f32 v75, v75, s52, v216
	v_fma_f32 v76, v76, s52, v216
	v_fma_f32 v77, v77, s52, v216
	v_fma_f32 v78, v78, s52, v216
	v_fma_f32 v79, v79, s52, v216
	v_fma_f32 v80, v80, s52, v216
	v_fma_f32 v81, v81, s52, v216
	v_fma_f32 v82, v82, s52, v216
	v_fma_f32 v83, v83, s52, v216
	v_fma_f32 v84, v84, s52, v216
	v_fma_f32 v85, v85, s52, v216
	v_fma_f32 v86, v86, s52, v216
	v_fma_f32 v87, v87, s52, v216
	v_fma_f32 v88, v88, s52, v216
	v_fma_f32 v89, v89, s52, v216
	v_fma_f32 v90, v90, s52, v216
	v_fma_f32 v91, v91, s52, v216
	v_fma_f32 v92, v92, s52, v216
	v_fma_f32 v93, v93, s52, v216
	v_fma_f32 v94, v94, s52, v216
	v_fma_f32 v95, v95, s52, v216
	v_fma_f32 v96, v96, s52, v216
	v_fma_f32 v97, v97, s52, v216
	v_exp_f32_e32 v66, v66
	v_exp_f32_e32 v67, v67
	v_exp_f32_e32 v68, v68
	v_exp_f32_e32 v69, v69
	v_exp_f32_e32 v70, v70
	v_exp_f32_e32 v71, v71
	v_exp_f32_e32 v72, v72
	v_exp_f32_e32 v73, v73
	v_exp_f32_e32 v74, v74
	v_exp_f32_e32 v75, v75
	v_exp_f32_e32 v76, v76
	v_exp_f32_e32 v77, v77
	v_exp_f32_e32 v78, v78
	v_exp_f32_e32 v79, v79
	v_exp_f32_e32 v80, v80
	v_exp_f32_e32 v81, v81
	v_exp_f32_e32 v82, v82
	v_exp_f32_e32 v83, v83
	v_exp_f32_e32 v84, v84
	v_exp_f32_e32 v85, v85
	v_exp_f32_e32 v86, v86
	v_exp_f32_e32 v87, v87
	v_exp_f32_e32 v88, v88
	v_exp_f32_e32 v89, v89
	v_exp_f32_e32 v90, v90
	v_exp_f32_e32 v91, v91
	v_exp_f32_e32 v92, v92
	v_exp_f32_e32 v93, v93
	v_exp_f32_e32 v94, v94
	v_exp_f32_e32 v95, v95
	v_exp_f32_e32 v96, v96
	v_exp_f32_e32 v97, v97
	v_add_f32_e32 v212, v66, v68
	v_add_f32_e32 v213, v67, v69
	v_add_f32_e32 v212, v70, v212
	v_add_f32_e32 v213, v71, v213
	v_add_f32_e32 v212, v72, v212
	v_add_f32_e32 v213, v73, v213
	v_add_f32_e32 v212, v74, v212
	v_add_f32_e32 v213, v75, v213
	v_add_f32_e32 v212, v76, v212
	v_add_f32_e32 v213, v77, v213
	v_add_f32_e32 v212, v78, v212
	v_add_f32_e32 v213, v79, v213
	v_add_f32_e32 v212, v80, v212
	v_add_f32_e32 v213, v81, v213
	v_add_f32_e32 v212, v82, v212
	v_add_f32_e32 v213, v83, v213
	v_add_f32_e32 v212, v84, v212
	v_add_f32_e32 v213, v85, v213
	v_add_f32_e32 v212, v86, v212
	v_add_f32_e32 v213, v87, v213
	v_add_f32_e32 v212, v88, v212
	v_add_f32_e32 v213, v89, v213
	v_add_f32_e32 v212, v90, v212
	v_add_f32_e32 v213, v91, v213
	v_add_f32_e32 v212, v92, v212
	v_add_f32_e32 v213, v93, v213
	v_add_f32_e32 v212, v94, v212
	v_add_f32_e32 v213, v95, v213
	v_add_f32_e32 v212, v96, v212
	v_add_f32_e32 v213, v97, v213
	v_add_f32_e64 v212, v212, v213
	v_fma_f32 v254, v254, v215, v212
	v_cvt_pk_bf16_f32 v66, v66, v67
	v_cvt_pk_bf16_f32 v67, v68, v69
	v_cvt_pk_bf16_f32 v68, v70, v71
	v_cvt_pk_bf16_f32 v69, v72, v73
	v_cvt_pk_bf16_f32 v70, v74, v75
	v_cvt_pk_bf16_f32 v71, v76, v77
	v_cvt_pk_bf16_f32 v72, v78, v79
	v_cvt_pk_bf16_f32 v73, v80, v81
	v_cvt_pk_bf16_f32 v82, v82, v83
	v_cvt_pk_bf16_f32 v83, v84, v85
	v_cvt_pk_bf16_f32 v84, v86, v87
	v_cvt_pk_bf16_f32 v85, v88, v89
	v_cvt_pk_bf16_f32 v86, v90, v91
	v_cvt_pk_bf16_f32 v87, v92, v93
	v_cvt_pk_bf16_f32 v88, v94, v95
	v_cvt_pk_bf16_f32 v89, v96, v97
	v_permlane32_swap_b32_e32 v66, v68
	v_permlane32_swap_b32_e32 v67, v69
	v_permlane32_swap_b32_e32 v70, v72
	v_permlane32_swap_b32_e32 v71, v73
	v_permlane32_swap_b32_e32 v82, v84
	v_permlane32_swap_b32_e32 v83, v85
	v_permlane32_swap_b32_e32 v86, v88
	v_permlane32_swap_b32_e32 v87, v89
	v_cmp_gt_f32_e32 vcc, 1.0, v215
	s_cbranch_vccnz .LA_slow0

; __device__ __forceinline__ void partialSM(f32x16& p0, f32x16& p1, float& m_reg, float& mn, float& alpha) {
;     constexpr float Cc = SCALE * 1.4426950408889634f;
;     float pmax = p0[0];
; #pragma unroll
;     for (int r = 1; r < 16; ++r) pmax = fmaxf(pmax, p0[r]);
; #pragma unroll
;     for (int r = 0; r < 16; ++r) pmax = fmaxf(pmax, p1[r]);
;     { auto rr = __builtin_amdgcn_permlane32_swap(__float_as_uint(pmax), __float_as_uint(pmax), false, false);
;       pmax = fmaxf(__uint_as_float(rr[0]), __uint_as_float(rr[1])); }
;     if (__builtin_expect(__all(pmax - m_reg <= THR / SCALE), 1)) { mn = m_reg; alpha = 1.f; }
;     else { mn = fmaxf(m_reg, pmax); alpha = __builtin_amdgcn_exp2f((m_reg - mn) * Cc); m_reg = mn; }
;     const float mnC = -mn * Cc;
;     { typedef float f32x2 __attribute__((ext_vector_type(2))); const f32x2 c2 = {Cc, Cc}, m2 = {mnC, mnC};
; #pragma unroll
;       for (int r = 0; r < 16; r += 2) { f32x2 t = {p0[r], p0[r + 1]}; t = __builtin_elementwise_fma(t, c2, m2); p0[r] = t.x; p0[r + 1] = t.y; }
; #pragma unroll
;       for (int r = 0; r < 16; r += 2) { f32x2 t = {p1[r], p1[r + 1]}; t = __builtin_elementwise_fma(t, c2, m2); p1[r] = t.x; p1[r + 1] = t.y; } }
; #pragma unroll
;     for (int r = 0; r < 16; ++r) p0[r] = __builtin_amdgcn_exp2f(p0[r]);
; }
; __device__ __forceinline__ void finishSM(f32x16& p0, f32x16& p1, float alpha, float& l_reg, bf16x8& pa0, bf16x8& pa1, bf16x8& pa2, bf16x8& pa3) {
; #pragma unroll
;     for (int r = 0; r < 16; ++r) p1[r] = __builtin_amdgcn_exp2f(p1[r]);
;     float ps;
;     { typedef float f32x2 __attribute__((ext_vector_type(2))); f32x2 s0 = {p0[0], p0[1]}, s1 = {p1[0], p1[1]};
; #pragma unroll
;       for (int r = 2; r < 16; r += 2) { s0 += (f32x2){p0[r], p0[r + 1]}; s1 += (f32x2){p1[r], p1[r + 1]}; }
;       s0 += s1; ps = s0.x + s0.y; }
;     { auto rr = __builtin_amdgcn_permlane32_swap(__float_as_uint(ps), __float_as_uint(ps), false, false);
;       ps = __uint_as_float(rr[0]) + __uint_as_float(rr[1]); }
;     l_reg = l_reg * alpha + ps;
;     ...
;     PK4(p0, 0, pa0); PK4(p0, 8, pa1); PK4(p1, 0, pa2); PK4(p1, 8, pa3);
.LA_g1b:
	ds_read_b64_tr_b16 v[74:75], v202 offset:0
	ds_read_b64_tr_b16 v[76:77], v202 offset:2048
	ds_read_b64_tr_b16 v[78:79], v202 offset:4096
	ds_read_b64_tr_b16 v[80:81], v202 offset:6144
	ds_read_b64_tr_b16 v[90:91], v202 offset:8192
	ds_read_b64_tr_b16 v[92:93], v202 offset:10240
	ds_read_b64_tr_b16 v[94:95], v202 offset:12288
	ds_read_b64_tr_b16 v[96:97], v202 offset:14336
	v_max_f32_e32 v212, v98, v99
	v_max_f32_e32 v213, v114, v115
	v_max3_f32 v212, v212, v100, v101
	v_max3_f32 v213, v213, v116, v117
	v_max3_f32 v212, v212, v102, v103
	v_max3_f32 v213, v213, v118, v119
	v_max3_f32 v212, v212, v104, v105
	v_max3_f32 v213, v213, v120, v121
	v_max3_f32 v212, v212, v106, v107
	v_max3_f32 v213, v213, v122, v123
	v_max3_f32 v212, v212, v108, v109
	v_max3_f32 v213, v213, v124, v125
	v_max3_f32 v212, v212, v110, v111
	v_max3_f32 v213, v213, v126, v127
	v_max3_f32 v212, v212, v112, v113
	v_max3_f32 v213, v213, v128, v129
	v_max_f32_e32 v212, v212, v213
	v_mov_b32_e32 v213, v212
	s_nop 1
	v_permlane32_swap_b32_e32 v212, v213
	v_max_f32_e32 v212, v212, v213
	v_sub_f32_e32 v214, v212, v139
	v_cmp_ge_f32_e32 vcc, s67, v214
	v_max_f32_e32 v212, v139, v212
	v_sub_f32_e64 v214, v139, v212
	v_mul_f32_e32 v214, 0x3e16c740, v214
	v_exp_f32_e64 v215, v214
	s_cmp_eq_u64 vcc, exec
	s_cselect_b64 s[58:59], -1, 0
	v_cndmask_b32_e64 v139, v212, v139, s[58:59]
	v_cndmask_b32_e64 v215, v215, 1.0, s[58:59]
	v_mul_f32_e32 v216, 0xbe16c740, v139
	v_fma_f32 v98, v98, s52, v216
	v_fma_f32 v99, v99, s52, v216
	v_fma_f32 v100, v100, s52, v216
	v_fma_f32 v101, v101, s52, v216
	v_fma_f32 v102, v102, s52, v216
	v_fma_f32 v103, v103, s52, v216
	v_fma_f32 v104, v104, s52, v216
	v_fma_f32 v105, v105, s52, v216
	v_fma_f32 v106, v106, s52, v216
	v_fma_f32 v107, v107, s52, v216
	v_fma_f32 v108, v108, s52, v216
	v_fma_f32 v109, v109, s52, v216
	v_fma_f32 v110, v110, s52, v216
	v_fma_f32 v111, v111, s52, v216
	v_fma_f32 v112, v112, s52, v216
	v_fma_f32 v113, v113, s52, v216
	v_fma_f32 v114, v114, s52, v216
	v_fma_f32 v115, v115, s52, v216
	v_fma_f32 v116, v116, s52, v216
	v_fma_f32 v117, v117, s52, v216
	v_fma_f32 v118, v118, s52, v216
	v_fma_f32 v119, v119, s52, v216
	v_fma_f32 v120, v120, s52, v216
	v_fma_f32 v121, v121, s52, v216
	v_fma_f32 v122, v122, s52, v216
	v_fma_f32 v123, v123, s52, v216
	v_fma_f32 v124, v124, s52, v216
	v_fma_f32 v125, v125, s52, v216
	v_fma_f32 v126, v126, s52, v216
	v_fma_f32 v127, v127, s52, v216
	v_fma_f32 v128, v128, s52, v216
	v_fma_f32 v129, v129, s52, v216
	v_exp_f32_e32 v98, v98
	v_exp_f32_e32 v99, v99
	v_exp_f32_e32 v100, v100
	v_exp_f32_e32 v101, v101
	v_exp_f32_e32 v102, v102
	v_exp_f32_e32 v103, v103
	v_exp_f32_e32 v104, v104
	v_exp_f32_e32 v105, v105
	v_exp_f32_e32 v106, v106
	v_exp_f32_e32 v107, v107
	v_exp_f32_e32 v108, v108
	v_exp_f32_e32 v109, v109
	v_exp_f32_e32 v110, v110
	v_exp_f32_e32 v111, v111
	v_exp_f32_e32 v112, v112
	v_exp_f32_e32 v113, v113
	v_exp_f32_e32 v114, v114
	v_exp_f32_e32 v115, v115
	v_exp_f32_e32 v116, v116
	v_exp_f32_e32 v117, v117
	v_exp_f32_e32 v118, v118
	v_exp_f32_e32 v119, v119
	v_exp_f32_e32 v120, v120
	v_exp_f32_e32 v121, v121
	v_exp_f32_e32 v122, v122
	v_exp_f32_e32 v123, v123
	v_exp_f32_e32 v124, v124
	v_exp_f32_e32 v125, v125
	v_exp_f32_e32 v126, v126
	v_exp_f32_e32 v127, v127
	v_exp_f32_e32 v128, v128
	v_exp_f32_e32 v129, v129
	v_add_f32_e32 v212, v98, v100
	v_add_f32_e32 v213, v99, v101
	v_add_f32_e32 v212, v102, v212
	v_add_f32_e32 v213, v103, v213
	v_add_f32_e32 v212, v104, v212
	v_add_f32_e32 v213, v105, v213
	v_add_f32_e32 v212, v106, v212
	v_add_f32_e32 v213, v107, v213
	v_add_f32_e32 v212, v108, v212
	v_add_f32_e32 v213, v109, v213
	v_add_f32_e32 v212, v110, v212
	v_add_f32_e32 v213, v111, v213
	v_add_f32_e32 v212, v112, v212
	v_add_f32_e32 v213, v113, v213
	v_add_f32_e32 v212, v114, v212
	v_add_f32_e32 v213, v115, v213
	v_add_f32_e32 v212, v116, v212
	v_add_f32_e32 v213, v117, v213
	v_add_f32_e32 v212, v118, v212
	v_add_f32_e32 v213, v119, v213
	v_add_f32_e32 v212, v120, v212
	v_add_f32_e32 v213, v121, v213
	v_add_f32_e32 v212, v122, v212
	v_add_f32_e32 v213, v123, v213
	v_add_f32_e32 v212, v124, v212
	v_add_f32_e32 v213, v125, v213
	v_add_f32_e32 v212, v126, v212
	v_add_f32_e32 v213, v127, v213
	v_add_f32_e32 v212, v128, v212
	v_add_f32_e32 v213, v129, v213
	v_add_f32_e64 v212, v212, v213
	v_fma_f32 v255, v255, v215, v212
	v_cvt_pk_bf16_f32 v98, v98, v99
	v_cvt_pk_bf16_f32 v99, v100, v101
	v_cvt_pk_bf16_f32 v100, v102, v103
	v_cvt_pk_bf16_f32 v101, v104, v105
	v_cvt_pk_bf16_f32 v102, v106, v107
	v_cvt_pk_bf16_f32 v103, v108, v109
	v_cvt_pk_bf16_f32 v104, v110, v111
	v_cvt_pk_bf16_f32 v105, v112, v113
	v_cvt_pk_bf16_f32 v114, v114, v115
	v_cvt_pk_bf16_f32 v115, v116, v117
	v_cvt_pk_bf16_f32 v116, v118, v119
	v_cvt_pk_bf16_f32 v117, v120, v121
	v_cvt_pk_bf16_f32 v118, v122, v123
	v_cvt_pk_bf16_f32 v119, v124, v125
	v_cvt_pk_bf16_f32 v120, v126, v127
	v_cvt_pk_bf16_f32 v121, v128, v129
	v_permlane32_swap_b32_e32 v98, v100
	v_permlane32_swap_b32_e32 v99, v101
	v_permlane32_swap_b32_e32 v102, v104
	v_permlane32_swap_b32_e32 v103, v105
	v_permlane32_swap_b32_e32 v114, v116
	v_permlane32_swap_b32_e32 v115, v117
	v_permlane32_swap_b32_e32 v118, v120
	v_permlane32_swap_b32_e32 v119, v121
	v_cmp_gt_f32_e32 vcc, 1.0, v215
	s_cbranch_vccnz .LA_slow1

; __device__ __forceinline__ unsigned f2bf(float f) { unsigned u = __builtin_bit_cast(unsigned, f); return (u + 0x7fffu + ((u >> 16) & 1u)) >> 16; }
; __device__ __forceinline__ int crow(int r, int hi) { return (r & 3) + 8 * (r >> 2) + 4 * hi; }
; __device__ __forceinline__ void attn_body(const bf16_t* __restrict__ Qb, const bf16_t* __restrict__ KVh, const bf16_t* __restrict__ KR, const float* __restrict__ ropeq,
;                                           bf16_t* __restrict__ Ob, int seq, char* lds, const int tid) {
;     ...
;     if (hi == 0) li_l[r32] = l_reg; asm volatile("s_waitcnt lgkmcnt(0)" ::: "memory");
;     float rli[16];
; #pragma unroll
;     for (int r = 0; r < 16; ++r) rli[r] = __builtin_amdgcn_rcpf(li_l[crow(r, hi)]);
;     bf16_t* Ow = Ob + (size_t)(wid * QBLK) * DM;
; #pragma unroll
;     for (int r = 0; r < 16; ++r) { const int orow = crow(r, hi);
; #pragma unroll
;         for (int d0 = 0; d0 < 2; ++d0) Ow[(size_t)orow * DM + d0 * 32 + r32] = (bf16_t)f2bf(o[d0][r] * rli[r]); }
.LA_g0b:
	s_add_i32 s16, s16, 1
	s_mov_b32 s17, s18
	s_mov_b32 s18, s19
	s_mov_b32 s19, s22
	s_mov_b32 s22, s17
	s_cmp_lt_u32 s16, 64
	s_cbranch_scc1 .LA_loop
	s_branch .LA_lexit
.LA_slow0:
	s_and_saveexec_b64 s[60:61], s[4:5]
	ds_write_b32 v234, v215 offset:128
	s_or_b64 exec, exec, s[60:61]
	s_waitcnt lgkmcnt(0)
	v_add_u32_e32 v245, v232, v233
	ds_read_b128 v[220:223], v245 offset:224
	ds_read_b128 v[224:227], v245 offset:192
	ds_read_b128 v[216:219], v245 offset:160
	ds_read_b128 v[212:215], v245 offset:128
	s_waitcnt lgkmcnt(0)
	v_mul_f32_e32 v12, v12, v220
	v_mul_f32_e32 v13, v13, v221
	v_mul_f32_e32 v14, v14, v222
	v_mul_f32_e32 v15, v15, v223
	v_mul_f32_e32 v8, v8, v224
	v_mul_f32_e32 v9, v9, v225
	v_mul_f32_e32 v10, v10, v226
	v_mul_f32_e32 v11, v11, v227
	v_mul_f32_e32 v4, v4, v216
	v_mul_f32_e32 v5, v5, v217
	v_mul_f32_e32 v6, v6, v218
	v_mul_f32_e32 v7, v7, v219
	v_mul_f32_e32 v0, v0, v212
	v_mul_f32_e32 v1, v1, v213
	v_mul_f32_e32 v2, v2, v214
	v_mul_f32_e32 v3, v3, v215
	v_mul_f32_e32 v28, v28, v220
	v_mul_f32_e32 v29, v29, v221
	v_mul_f32_e32 v30, v30, v222
	v_mul_f32_e32 v31, v31, v223
	v_mul_f32_e32 v24, v24, v224
	v_mul_f32_e32 v25, v25, v225
	v_mul_f32_e32 v26, v26, v226
	v_mul_f32_e32 v27, v27, v227
	v_mul_f32_e32 v20, v20, v216
	v_mul_f32_e32 v21, v21, v217
	v_mul_f32_e32 v22, v22, v218
	v_mul_f32_e32 v23, v23, v219
	v_mul_f32_e32 v16, v16, v212
	v_mul_f32_e32 v17, v17, v213
	v_mul_f32_e32 v18, v18, v214
	v_mul_f32_e32 v19, v19, v215
	s_nop 1
	s_branch .LA_rs0
.LA_slow1:
	s_and_saveexec_b64 s[60:61], s[4:5]
	ds_write_b32 v234, v215 offset:128
	s_or_b64 exec, exec, s[60:61]
	s_waitcnt lgkmcnt(0)
	v_add_u32_e32 v245, v232, v233
	ds_read_b128 v[220:223], v245 offset:224
	ds_read_b128 v[224:227], v245 offset:192
	ds_read_b128 v[216:219], v245 offset:160
	ds_read_b128 v[212:215], v245 offset:128
	s_waitcnt lgkmcnt(0)
	v_mul_f32_e32 v44, v44, v220
	v_mul_f32_e32 v45, v45, v221
	v_mul_f32_e32 v46, v46, v222
	v_mul_f32_e32 v47, v47, v223
	v_mul_f32_e32 v40, v40, v224
	v_mul_f32_e32 v41, v41, v225
	v_mul_f32_e32 v42, v42, v226
	v_mul_f32_e32 v43, v43, v227
	v_mul_f32_e32 v36, v36, v216
	v_mul_f32_e32 v37, v37, v217
	v_mul_f32_e32 v38, v38, v218
	v_mul_f32_e32 v39, v39, v219
	v_mul_f32_e32 v32, v32, v212
	v_mul_f32_e32 v33, v33, v213
	v_mul_f32_e32 v34, v34, v214
	v_mul_f32_e32 v35, v35, v215
	v_mul_f32_e32 v60, v60, v220
	v_mul_f32_e32 v61, v61, v221
	v_mul_f32_e32 v62, v62, v222
	v_mul_f32_e32 v63, v63, v223
	v_mul_f32_e32 v56, v56, v224
	v_mul_f32_e32 v57, v57, v225
	v_mul_f32_e32 v58, v58, v226
	v_mul_f32_e32 v59, v59, v227
	v_mul_f32_e32 v52, v52, v216
	v_mul_f32_e32 v53, v53, v217
	v_mul_f32_e32 v54, v54, v218
	v_mul_f32_e32 v55, v55, v219
	v_mul_f32_e32 v48, v48, v212
	v_mul_f32_e32 v49, v49, v213
	v_mul_f32_e32 v50, v50, v214
	v_mul_f32_e32 v51, v51, v215
	s_nop 1
	s_branch .LA_rs1
.LA_lexit:
	v_and_b32_e32 v245, 31, v211
	v_lshrrev_b32_e32 v246, 5, v211
	v_lshlrev_b32_e32 v202, 1, v245
	v_lshl_add_u32 v202, v246, 13, v202
	v_mov_b32_e32 v203, v254
	s_nop 1
	v_permlane32_swap_b32_e32 v254, v203
	v_add_f32_e32 v254, v254, v203
	s_and_saveexec_b64 s[60:61], s[4:5]
	ds_write_b32 v234, v254
	s_or_b64 exec, exec, s[60:61]
	s_waitcnt lgkmcnt(0)
	v_add_u32_e32 v245, v232, v233
	ds_read_b128 v[212:215], v245 offset:0
	ds_read_b128 v[216:219], v245 offset:32
	ds_read_b128 v[220:223], v245 offset:64
	ds_read_b128 v[224:227], v245 offset:96
	s_waitcnt lgkmcnt(0)
	v_rcp_f32_e32 v212, v212
	v_rcp_f32_e32 v213, v213
	v_rcp_f32_e32 v214, v214
	v_rcp_f32_e32 v215, v215
	v_rcp_f32_e32 v216, v216
	v_rcp_f32_e32 v217, v217
	v_rcp_f32_e32 v218, v218
	v_rcp_f32_e32 v219, v219
	v_rcp_f32_e32 v220, v220
	v_rcp_f32_e32 v221, v221
	v_rcp_f32_e32 v222, v222
	v_rcp_f32_e32 v223, v223
	v_rcp_f32_e32 v224, v224
	v_rcp_f32_e32 v225, v225
	v_rcp_f32_e32 v226, v226
	v_rcp_f32_e32 v227, v227
	v_add_u32_e32 v246, 0x0, v202
	v_mul_f32_e32 v0, v0, v212
	v_bfe_u32 v247, v0, 16, 1
	v_add3_u32 v0, v0, v247, s33
	global_store_short_d16_hi v246, v0, s[42:43] offset:0
	v_mul_f32_e32 v16, v16, v212
	v_bfe_u32 v247, v16, 16, 1
	v_add3_u32 v16, v16, v247, s33
	global_store_short_d16_hi v246, v16, s[42:43] offset:64
	v_mul_f32_e32 v1, v1, v213
	v_bfe_u32 v247, v1, 16, 1
	v_add3_u32 v1, v1, v247, s33
	global_store_short_d16_hi v246, v1, s[42:43] offset:2048
	v_mul_f32_e32 v17, v17, v213
	v_bfe_u32 v247, v17, 16, 1
	v_add3_u32 v17, v17, v247, s33
	global_store_short_d16_hi v246, v17, s[42:43] offset:2112
	v_add_u32_e32 v246, 0x1000, v202
	v_mul_f32_e32 v2, v2, v214
	v_bfe_u32 v247, v2, 16, 1
	v_add3_u32 v2, v2, v247, s33
	global_store_short_d16_hi v246, v2, s[42:43] offset:0
	v_mul_f32_e32 v18, v18, v214
	v_bfe_u32 v247, v18, 16, 1
	v_add3_u32 v18, v18, v247, s33
	global_store_short_d16_hi v246, v18, s[42:43] offset:64
	v_mul_f32_e32 v3, v3, v215
	v_bfe_u32 v247, v3, 16, 1
	v_add3_u32 v3, v3, v247, s33
	global_store_short_d16_hi v246, v3, s[42:43] offset:2048
	v_mul_f32_e32 v19, v19, v215
	v_bfe_u32 v247, v19, 16, 1
	v_add3_u32 v19, v19, v247, s33
	global_store_short_d16_hi v246, v19, s[42:43] offset:2112
	v_add_u32_e32 v246, 0x4000, v202
	v_mul_f32_e32 v4, v4, v216
	v_bfe_u32 v247, v4, 16, 1
	v_add3_u32 v4, v4, v247, s33
	global_store_short_d16_hi v246, v4, s[42:43] offset:0
	v_mul_f32_e32 v20, v20, v216
	v_bfe_u32 v247, v20, 16, 1
	v_add3_u32 v20, v20, v247, s33
	global_store_short_d16_hi v246, v20, s[42:43] offset:64
	v_mul_f32_e32 v5, v5, v217
	v_bfe_u32 v247, v5, 16, 1
	v_add3_u32 v5, v5, v247, s33
	global_store_short_d16_hi v246, v5, s[42:43] offset:2048
	v_mul_f32_e32 v21, v21, v217
	v_bfe_u32 v247, v21, 16, 1
	v_add3_u32 v21, v21, v247, s33
; __device__ __forceinline__ unsigned f2bf(float f) { unsigned u = __builtin_bit_cast(unsigned, f); return (u + 0x7fffu + ((u >> 16) & 1u)) >> 16; }
; __device__ __forceinline__ int crow(int r, int hi) { return (r & 3) + 8 * (r >> 2) + 4 * hi; }
; __device__ __forceinline__ void attn_body(const bf16_t* __restrict__ Qb, const bf16_t* __restrict__ KVh, const bf16_t* __restrict__ KR, const float* __restrict__ ropeq,
;                                           bf16_t* __restrict__ Ob, int seq, char* lds, const int tid) {
;     ...
;     if (hi == 0) li_l[r32] = l_reg; asm volatile("s_waitcnt lgkmcnt(0)" ::: "memory");
;     float rli[16];
; #pragma unroll
;     for (int r = 0; r < 16; ++r) rli[r] = __builtin_amdgcn_rcpf(li_l[crow(r, hi)]);
;     bf16_t* Ow = Ob + (size_t)(wid * QBLK) * DM;
; #pragma unroll
;     for (int r = 0; r < 16; ++r) { const int orow = crow(r, hi);
; #pragma unroll
;         for (int d0 = 0; d0 < 2; ++d0) Ow[(size_t)orow * DM + d0 * 32 + r32] = (bf16_t)f2bf(o[d0][r] * rli[r]); }
	global_store_short_d16_hi v246, v21, s[42:43] offset:2112
	v_add_u32_e32 v246, 0x5000, v202
	v_mul_f32_e32 v6, v6, v218
	v_bfe_u32 v247, v6, 16, 1
	v_add3_u32 v6, v6, v247, s33
	global_store_short_d16_hi v246, v6, s[42:43] offset:0
	v_mul_f32_e32 v22, v22, v218
	v_bfe_u32 v247, v22, 16, 1
	v_add3_u32 v22, v22, v247, s33
	global_store_short_d16_hi v246, v22, s[42:43] offset:64
	v_mul_f32_e32 v7, v7, v219
	v_bfe_u32 v247, v7, 16, 1
	v_add3_u32 v7, v7, v247, s33
	global_store_short_d16_hi v246, v7, s[42:43] offset:2048
	v_mul_f32_e32 v23, v23, v219
	v_bfe_u32 v247, v23, 16, 1
	v_add3_u32 v23, v23, v247, s33
	global_store_short_d16_hi v246, v23, s[42:43] offset:2112
	v_add_u32_e32 v246, 0x8000, v202
	v_mul_f32_e32 v8, v8, v220
	v_bfe_u32 v247, v8, 16, 1
	v_add3_u32 v8, v8, v247, s33
	global_store_short_d16_hi v246, v8, s[42:43] offset:0
	v_mul_f32_e32 v24, v24, v220
	v_bfe_u32 v247, v24, 16, 1
	v_add3_u32 v24, v24, v247, s33
	global_store_short_d16_hi v246, v24, s[42:43] offset:64
	v_mul_f32_e32 v9, v9, v221
	v_bfe_u32 v247, v9, 16, 1
	v_add3_u32 v9, v9, v247, s33
	global_store_short_d16_hi v246, v9, s[42:43] offset:2048
	v_mul_f32_e32 v25, v25, v221
	v_bfe_u32 v247, v25, 16, 1
	v_add3_u32 v25, v25, v247, s33
	global_store_short_d16_hi v246, v25, s[42:43] offset:2112
	v_add_u32_e32 v246, 0x9000, v202
	v_mul_f32_e32 v10, v10, v222
	v_bfe_u32 v247, v10, 16, 1
	v_add3_u32 v10, v10, v247, s33
	global_store_short_d16_hi v246, v10, s[42:43] offset:0
	v_mul_f32_e32 v26, v26, v222
	v_bfe_u32 v247, v26, 16, 1
	v_add3_u32 v26, v26, v247, s33
	global_store_short_d16_hi v246, v26, s[42:43] offset:64
	v_mul_f32_e32 v11, v11, v223
	v_bfe_u32 v247, v11, 16, 1
	v_add3_u32 v11, v11, v247, s33
	global_store_short_d16_hi v246, v11, s[42:43] offset:2048
	v_mul_f32_e32 v27, v27, v223
	v_bfe_u32 v247, v27, 16, 1
	v_add3_u32 v27, v27, v247, s33
	global_store_short_d16_hi v246, v27, s[42:43] offset:2112
	v_add_u32_e32 v246, 0xc000, v202
	v_mul_f32_e32 v12, v12, v224
	v_bfe_u32 v247, v12, 16, 1
	v_add3_u32 v12, v12, v247, s33
	global_store_short_d16_hi v246, v12, s[42:43] offset:0
	v_mul_f32_e32 v28, v28, v224
	v_bfe_u32 v247, v28, 16, 1
	v_add3_u32 v28, v28, v247, s33
	global_store_short_d16_hi v246, v28, s[42:43] offset:64
	v_mul_f32_e32 v13, v13, v225
	v_bfe_u32 v247, v13, 16, 1
	v_add3_u32 v13, v13, v247, s33
	global_store_short_d16_hi v246, v13, s[42:43] offset:2048
	v_mul_f32_e32 v29, v29, v225
	v_bfe_u32 v247, v29, 16, 1
	v_add3_u32 v29, v29, v247, s33
	global_store_short_d16_hi v246, v29, s[42:43] offset:2112
	v_add_u32_e32 v246, 0xd000, v202
	v_mul_f32_e32 v14, v14, v226
	v_bfe_u32 v247, v14, 16, 1
	v_add3_u32 v14, v14, v247, s33
	global_store_short_d16_hi v246, v14, s[42:43] offset:0
	v_mul_f32_e32 v30, v30, v226
	v_bfe_u32 v247, v30, 16, 1
	v_add3_u32 v30, v30, v247, s33
	global_store_short_d16_hi v246, v30, s[42:43] offset:64
	v_mul_f32_e32 v15, v15, v227
	v_bfe_u32 v247, v15, 16, 1
	v_add3_u32 v15, v15, v247, s33
	global_store_short_d16_hi v246, v15, s[42:43] offset:2048
	v_mul_f32_e32 v31, v31, v227
	v_bfe_u32 v247, v31, 16, 1
	v_add3_u32 v31, v31, v247, s33
	global_store_short_d16_hi v246, v31, s[42:43] offset:2112
	s_waitcnt lgkmcnt(0)
	v_mov_b32_e32 v203, v255
	s_nop 1
	v_permlane32_swap_b32_e32 v255, v203
	v_add_f32_e32 v255, v255, v203
	s_and_saveexec_b64 s[60:61], s[4:5]
	ds_write_b32 v234, v255
	s_or_b64 exec, exec, s[60:61]
	s_waitcnt lgkmcnt(0)
	v_add_u32_e32 v245, v232, v233
	ds_read_b128 v[212:215], v245 offset:0
	ds_read_b128 v[216:219], v245 offset:32
	ds_read_b128 v[220:223], v245 offset:64
	ds_read_b128 v[224:227], v245 offset:96
	s_waitcnt lgkmcnt(0)
; __device__ __forceinline__ unsigned f2bf(float f) { unsigned u = __builtin_bit_cast(unsigned, f); return (u + 0x7fffu + ((u >> 16) & 1u)) >> 16; }
; __device__ __forceinline__ int crow(int r, int hi) { return (r & 3) + 8 * (r >> 2) + 4 * hi; }
; __device__ __forceinline__ void attn_body(const bf16_t* __restrict__ Qb, const bf16_t* __restrict__ KVh, const bf16_t* __restrict__ KR, const float* __restrict__ ropeq,
;                                           bf16_t* __restrict__ Ob, int seq, char* lds, const int tid) {
;     ...
;     if (hi == 0) li_l[r32] = l_reg; asm volatile("s_waitcnt lgkmcnt(0)" ::: "memory");
;     float rli[16];
; #pragma unroll
;     for (int r = 0; r < 16; ++r) rli[r] = __builtin_amdgcn_rcpf(li_l[crow(r, hi)]);
;     bf16_t* Ow = Ob + (size_t)(wid * QBLK) * DM;
; #pragma unroll
;     for (int r = 0; r < 16; ++r) { const int orow = crow(r, hi);
; #pragma unroll
;         for (int d0 = 0; d0 < 2; ++d0) Ow[(size_t)orow * DM + d0 * 32 + r32] = (bf16_t)f2bf(o[d0][r] * rli[r]); }
; __device__ __forceinline__ void phase_attn(const Ctx& C, PP p, char* lds_generic) {
;     ...
;     for (int it = C.vcu; it < 2048; it += C.G) {
;         const int qb = it & 15, h = (it >> 4) & 15, b = it >> 8; const size_t t0 = (size_t)b * SEQ, q0 = t0 + qb * 256;
;         __syncthreads();
;         att::attn_body(Q + q0 * NQ + h * 96, KV + t0 * NKV + h * 128, KR + t0 * 32, rope + q0 * 32, O + q0 * DM + h * 64, SEQ, lds_generic, C.tid);
;     }
	v_rcp_f32_e32 v212, v212
	v_rcp_f32_e32 v213, v213
	v_rcp_f32_e32 v214, v214
	v_rcp_f32_e32 v215, v215
	v_rcp_f32_e32 v216, v216
	v_rcp_f32_e32 v217, v217
	v_rcp_f32_e32 v218, v218
	v_rcp_f32_e32 v219, v219
	v_rcp_f32_e32 v220, v220
	v_rcp_f32_e32 v221, v221
	v_rcp_f32_e32 v222, v222
	v_rcp_f32_e32 v223, v223
	v_rcp_f32_e32 v224, v224
	v_rcp_f32_e32 v225, v225
	v_rcp_f32_e32 v226, v226
	v_rcp_f32_e32 v227, v227
	v_add_u32_e32 v246, 0x10000, v202
	v_mul_f32_e32 v32, v32, v212
	v_bfe_u32 v247, v32, 16, 1
	v_add3_u32 v32, v32, v247, s33
	global_store_short_d16_hi v246, v32, s[42:43] offset:0
	v_mul_f32_e32 v48, v48, v212
	v_bfe_u32 v247, v48, 16, 1
	v_add3_u32 v48, v48, v247, s33
	global_store_short_d16_hi v246, v48, s[42:43] offset:64
	v_mul_f32_e32 v33, v33, v213
	v_bfe_u32 v247, v33, 16, 1
	v_add3_u32 v33, v33, v247, s33
	global_store_short_d16_hi v246, v33, s[42:43] offset:2048
	v_mul_f32_e32 v49, v49, v213
	v_bfe_u32 v247, v49, 16, 1
	v_add3_u32 v49, v49, v247, s33
	global_store_short_d16_hi v246, v49, s[42:43] offset:2112
	v_add_u32_e32 v246, 0x11000, v202
	v_mul_f32_e32 v34, v34, v214
	v_bfe_u32 v247, v34, 16, 1
	v_add3_u32 v34, v34, v247, s33
	global_store_short_d16_hi v246, v34, s[42:43] offset:0
	v_mul_f32_e32 v50, v50, v214
	v_bfe_u32 v247, v50, 16, 1
	v_add3_u32 v50, v50, v247, s33
	global_store_short_d16_hi v246, v50, s[42:43] offset:64
	v_mul_f32_e32 v35, v35, v215
	v_bfe_u32 v247, v35, 16, 1
	v_add3_u32 v35, v35, v247, s33
	global_store_short_d16_hi v246, v35, s[42:43] offset:2048
	v_mul_f32_e32 v51, v51, v215
	v_bfe_u32 v247, v51, 16, 1
	v_add3_u32 v51, v51, v247, s33
	global_store_short_d16_hi v246, v51, s[42:43] offset:2112
	v_add_u32_e32 v246, 0x14000, v202
	v_mul_f32_e32 v36, v36, v216
	v_bfe_u32 v247, v36, 16, 1
	v_add3_u32 v36, v36, v247, s33
	global_store_short_d16_hi v246, v36, s[42:43] offset:0
	v_mul_f32_e32 v52, v52, v216
	v_bfe_u32 v247, v52, 16, 1
	v_add3_u32 v52, v52, v247, s33
	global_store_short_d16_hi v246, v52, s[42:43] offset:64
	v_mul_f32_e32 v37, v37, v217
	v_bfe_u32 v247, v37, 16, 1
	v_add3_u32 v37, v37, v247, s33
	global_store_short_d16_hi v246, v37, s[42:43] offset:2048
	v_mul_f32_e32 v53, v53, v217
	v_bfe_u32 v247, v53, 16, 1
	v_add3_u32 v53, v53, v247, s33
	global_store_short_d16_hi v246, v53, s[42:43] offset:2112
	v_add_u32_e32 v246, 0x15000, v202
	v_mul_f32_e32 v38, v38, v218
	v_bfe_u32 v247, v38, 16, 1
	v_add3_u32 v38, v38, v247, s33
	global_store_short_d16_hi v246, v38, s[42:43] offset:0
	v_mul_f32_e32 v54, v54, v218
	v_bfe_u32 v247, v54, 16, 1
	v_add3_u32 v54, v54, v247, s33
	global_store_short_d16_hi v246, v54, s[42:43] offset:64
	v_mul_f32_e32 v39, v39, v219
	v_bfe_u32 v247, v39, 16, 1
	v_add3_u32 v39, v39, v247, s33
	global_store_short_d16_hi v246, v39, s[42:43] offset:2048
	v_mul_f32_e32 v55, v55, v219
	v_bfe_u32 v247, v55, 16, 1
	v_add3_u32 v55, v55, v247, s33
	global_store_short_d16_hi v246, v55, s[42:43] offset:2112
	v_add_u32_e32 v246, 0x18000, v202
	v_mul_f32_e32 v40, v40, v220
	v_bfe_u32 v247, v40, 16, 1
	v_add3_u32 v40, v40, v247, s33
	global_store_short_d16_hi v246, v40, s[42:43] offset:0
	v_mul_f32_e32 v56, v56, v220
	v_bfe_u32 v247, v56, 16, 1
	v_add3_u32 v56, v56, v247, s33
	global_store_short_d16_hi v246, v56, s[42:43] offset:64
	v_mul_f32_e32 v41, v41, v221
	v_bfe_u32 v247, v41, 16, 1
	v_add3_u32 v41, v41, v247, s33
	global_store_short_d16_hi v246, v41, s[42:43] offset:2048
	v_mul_f32_e32 v57, v57, v221
	v_bfe_u32 v247, v57, 16, 1
	v_add3_u32 v57, v57, v247, s33
	global_store_short_d16_hi v246, v57, s[42:43] offset:2112
	v_add_u32_e32 v246, 0x19000, v202
	v_mul_f32_e32 v42, v42, v222
	v_bfe_u32 v247, v42, 16, 1
	v_add3_u32 v42, v42, v247, s33
	global_store_short_d16_hi v246, v42, s[42:43] offset:0
	v_mul_f32_e32 v58, v58, v222
	v_bfe_u32 v247, v58, 16, 1
	v_add3_u32 v58, v58, v247, s33
	global_store_short_d16_hi v246, v58, s[42:43] offset:64
	v_mul_f32_e32 v43, v43, v223
	v_bfe_u32 v247, v43, 16, 1
	v_add3_u32 v43, v43, v247, s33
	global_store_short_d16_hi v246, v43, s[42:43] offset:2048
	v_mul_f32_e32 v59, v59, v223
	v_bfe_u32 v247, v59, 16, 1
	v_add3_u32 v59, v59, v247, s33
	global_store_short_d16_hi v246, v59, s[42:43] offset:2112
	v_add_u32_e32 v246, 0x1c000, v202
	v_mul_f32_e32 v44, v44, v224
	v_bfe_u32 v247, v44, 16, 1
	v_add3_u32 v44, v44, v247, s33
	global_store_short_d16_hi v246, v44, s[42:43] offset:0
	v_mul_f32_e32 v60, v60, v224
	v_bfe_u32 v247, v60, 16, 1
	v_add3_u32 v60, v60, v247, s33
	global_store_short_d16_hi v246, v60, s[42:43] offset:64
	v_mul_f32_e32 v45, v45, v225
	v_bfe_u32 v247, v45, 16, 1
	v_add3_u32 v45, v45, v247, s33
	global_store_short_d16_hi v246, v45, s[42:43] offset:2048
	v_mul_f32_e32 v61, v61, v225
	v_bfe_u32 v247, v61, 16, 1
	v_add3_u32 v61, v61, v247, s33
	global_store_short_d16_hi v246, v61, s[42:43] offset:2112
	v_add_u32_e32 v246, 0x1d000, v202
	v_mul_f32_e32 v46, v46, v226
	v_bfe_u32 v247, v46, 16, 1
	v_add3_u32 v46, v46, v247, s33
	global_store_short_d16_hi v246, v46, s[42:43] offset:0
	v_mul_f32_e32 v62, v62, v226
	v_bfe_u32 v247, v62, 16, 1
	v_add3_u32 v62, v62, v247, s33
	global_store_short_d16_hi v246, v62, s[42:43] offset:64
	v_mul_f32_e32 v47, v47, v227
	v_bfe_u32 v247, v47, 16, 1
	v_add3_u32 v47, v47, v247, s33
	global_store_short_d16_hi v246, v47, s[42:43] offset:2048
	v_mul_f32_e32 v63, v63, v227
	v_bfe_u32 v247, v63, 16, 1
	v_add3_u32 v63, v63, v247, s33
	global_store_short_d16_hi v246, v63, s[42:43] offset:2112
	s_waitcnt lgkmcnt(0)
	s_add_i32 s20, s20, s85
	s_cmpk_lt_i32 s20, 0x400
	s_cbranch_scc1 .LA_item
	s_branch .LBB0_78
